# P8 residual epilogue also hand-rewritten (XG and no-XG variants), same lane-pair permutation + 2-group-ahead prefetch as P5
# speedup vs baseline: 1.0021x; 1.0018x over previous
.LBB0_1240:
	v_readlane_b32 s14, v254, 62
	v_readlane_b32 s15, v254, 63
	v_readlane_b32 s58, v254, 57
	v_readlane_b32 s59, v254, 58
	s_mov_b64 s[56:57], 0x5b000000
	v_readlane_b32 s24, v255, 0
	v_readlane_b32 s25, v255, 1
	s_and_b64 vcc, exec, s[14:15]
	s_cbranch_vccz .Lp8epi_noxg
	v_and_b32_e32 v192, 8, v219
	v_cmp_ne_u32_e64 s[90:91], 0, v192
	v_sub_u32_e32 v214, v1, v192
	v_lshlrev_b32_e32 v192, 1, v192
	s_lshl_b32 s94, s50, 8
	v_add3_u32 v215, v240, v192, s94
	v_sub_u32_e32 v180, v240, v192
	v_add3_u32 v180, v180, 16, s94
	v_lshlrev_b32_e32 v193, 14, v214
	v_lshl_add_u32 v206, v180, 2, v193
	v_add_u32_e32 v206, 0x20000, v206
	v_lshl_add_u32 v193, v215, 2, v193
	v_lshlrev_b32_e32 v207, 13, v214
	v_lshl_add_u32 v208, v180, 1, v207
	v_add_u32_e32 v208, 0x10000, v208
	v_lshl_add_u32 v207, v215, 1, v207
	v_lshlrev_b32_e32 v209, 2, v215
	v_lshlrev_b32_e32 v210, 2, v180
	global_load_dwordx4 v[148:151], v209, s[16:17]
	global_load_dwordx4 v[156:159], v210, s[16:17]
	global_load_dwordx4 v[152:155], v209, s[16:17] offset:512
	global_load_dwordx4 v[160:163], v210, s[16:17] offset:512
	s_lshl_b32 s94, s50, 4
	s_lshl_b32 s95, s34, 2
	s_add_i32 s94, s94, s95
	v_lshlrev_b32_e32 v211, 8, v1
	v_add_u32_e32 v211, s94, v211
	v_xor_b32_e32 v212, 16, v219
	v_lshlrev_b32_e32 v212, 2, v212
	v_xor_b32_e32 v213, 32, v219
	v_lshlrev_b32_e32 v213, 2, v213
	s_lshl_b32 s94, s51, 8
	s_lshl_b32 s94, s94, 14
	s_add_u32 s84, s48, s94
	s_addc_u32 s85, s49, 0
	global_load_dwordx4 v[60:63], v193, s[84:85]
	global_load_dwordx4 v[68:71], v206, s[84:85]
	global_load_dwordx4 v[76:79], v193, s[84:85] offset:512
	global_load_dwordx4 v[80:83], v206, s[84:85] offset:512
	s_lshl_b32 s94, s51, 8
	s_add_i32 s94, s94, 16
	s_lshl_b32 s94, s94, 14
	s_add_u32 s84, s48, s94
	s_addc_u32 s85, s49, 0
	global_load_dwordx4 v[172:175], v193, s[84:85]
	global_load_dwordx4 v[176:179], v206, s[84:85]
	global_load_dwordx4 v[182:185], v193, s[84:85] offset:512
	global_load_dwordx4 v[232:235], v206, s[84:85] offset:512
	v_mov_b32_dpp v164, v140 row_ror:8 row_mask:0xf bank_mask:0xf
	v_mov_b32_dpp v165, v141 row_ror:8 row_mask:0xf bank_mask:0xf
	v_mov_b32_dpp v166, v142 row_ror:8 row_mask:0xf bank_mask:0xf
	v_mov_b32_dpp v167, v143 row_ror:8 row_mask:0xf bank_mask:0xf
	v_cndmask_b32_e64 v140, v164, v144, s[90:91]
	v_cndmask_b32_e64 v141, v165, v145, s[90:91]
	v_cndmask_b32_e64 v142, v166, v146, s[90:91]
	v_cndmask_b32_e64 v143, v167, v147, s[90:91]
	v_cndmask_b32_e64 v144, v144, v164, s[90:91]
	v_cndmask_b32_e64 v145, v145, v165, s[90:91]
	v_cndmask_b32_e64 v146, v146, v166, s[90:91]
	v_cndmask_b32_e64 v147, v147, v167, s[90:91]
	v_mov_b32_dpp v164, v132 row_ror:8 row_mask:0xf bank_mask:0xf
	v_mov_b32_dpp v165, v133 row_ror:8 row_mask:0xf bank_mask:0xf
	v_mov_b32_dpp v166, v134 row_ror:8 row_mask:0xf bank_mask:0xf
	v_mov_b32_dpp v167, v135 row_ror:8 row_mask:0xf bank_mask:0xf
	v_cndmask_b32_e64 v132, v164, v136, s[90:91]
	v_cndmask_b32_e64 v133, v165, v137, s[90:91]
	v_cndmask_b32_e64 v134, v166, v138, s[90:91]
	v_cndmask_b32_e64 v135, v167, v139, s[90:91]
	v_cndmask_b32_e64 v136, v136, v164, s[90:91]
	v_cndmask_b32_e64 v137, v137, v165, s[90:91]
	v_cndmask_b32_e64 v138, v138, v166, s[90:91]
	v_cndmask_b32_e64 v139, v139, v167, s[90:91]
	s_lshl_b32 s94, s51, 8
	s_lshl_b32 s94, s94, 14
	s_add_u32 s86, s48, s94
	s_addc_u32 s87, s49, 0
	s_lshl_b32 s94, s51, 8
	s_lshl_b32 s94, s94, 13
	s_add_u32 s88, s12, s94
	s_addc_u32 s89, s13, 0
	s_lshl_b32 s94, s51, 8
	s_lshl_b32 s94, s94, 8
	s_add_u32 s92, s22, s94
	s_addc_u32 s93, s23, 0
	s_waitcnt vmcnt(4)
	v_pk_add_f32 v[144:145], v[144:145], v[60:61]
	v_pk_add_f32 v[146:147], v[146:147], v[62:63]
	v_pk_add_f32 v[140:141], v[140:141], v[68:69]
	v_pk_add_f32 v[142:143], v[142:143], v[70:71]
	global_store_dwordx4 v193, v[144:147], s[86:87]
	global_store_dwordx4 v206, v[140:143], s[86:87]
	v_mul_f32_e32 v214, v144, v144
	v_fmac_f32_e32 v214, v145, v145
	v_fmac_f32_e32 v214, v146, v146
	v_fmac_f32_e32 v214, v147, v147
	v_mul_f32_e32 v215, v140, v140
	v_fmac_f32_e32 v215, v141, v141
	v_fmac_f32_e32 v215, v142, v142
	v_fmac_f32_e32 v215, v143, v143
	v_pk_mul_f32 v[164:165], v[144:145], v[148:149]
	v_pk_mul_f32 v[166:167], v[146:147], v[150:151]
	v_cvt_pk_bf16_f32 v168, v164, v165
	v_cvt_pk_bf16_f32 v169, v166, v167
	global_store_dwordx2 v207, v[168:169], s[88:89]
	v_pk_mul_f32 v[164:165], v[140:141], v[156:157]
	v_pk_mul_f32 v[166:167], v[142:143], v[158:159]
	v_cvt_pk_bf16_f32 v170, v164, v165
	v_cvt_pk_bf16_f32 v171, v166, v167
	global_store_dwordx2 v208, v[170:171], s[88:89]
	v_pk_add_f32 v[136:137], v[136:137], v[76:77]
	v_pk_add_f32 v[138:139], v[138:139], v[78:79]
	v_pk_add_f32 v[132:133], v[132:133], v[80:81]
	v_pk_add_f32 v[134:135], v[134:135], v[82:83]
	global_store_dwordx4 v193, v[136:139], s[86:87] offset:512
	global_store_dwordx4 v206, v[132:135], s[86:87] offset:512
	v_fmac_f32_e32 v214, v136, v136
	v_fmac_f32_e32 v214, v137, v137
	v_fmac_f32_e32 v214, v138, v138
	v_fmac_f32_e32 v214, v139, v139
	v_fmac_f32_e32 v215, v132, v132
	v_fmac_f32_e32 v215, v133, v133
	v_fmac_f32_e32 v215, v134, v134
	v_fmac_f32_e32 v215, v135, v135
	v_pk_mul_f32 v[164:165], v[136:137], v[152:153]
	v_pk_mul_f32 v[166:167], v[138:139], v[154:155]
	v_cvt_pk_bf16_f32 v168, v164, v165
	v_cvt_pk_bf16_f32 v169, v166, v167
	global_store_dwordx2 v207, v[168:169], s[88:89] offset:256
	v_pk_mul_f32 v[164:165], v[132:133], v[160:161]
	v_pk_mul_f32 v[166:167], v[134:135], v[162:163]
	v_cvt_pk_bf16_f32 v170, v164, v165
	v_cvt_pk_bf16_f32 v171, v166, v167
	global_store_dwordx2 v208, v[170:171], s[88:89] offset:256
	s_nop 1
	v_add_f32_dpp v180, v214, v214 row_ror:8 row_mask:0xf bank_mask:0xf
	v_add_f32_dpp v192, v215, v215 row_ror:8 row_mask:0xf bank_mask:0xf
	v_cndmask_b32_e64 v214, v180, v192, s[90:91]
	ds_bpermute_b32 v215, v212, v214
	s_waitcnt lgkmcnt(0)
	v_add_f32_e32 v214, v214, v215
	ds_bpermute_b32 v215, v213, v214
	s_waitcnt lgkmcnt(0)
	v_add_f32_e32 v214, v214, v215
	s_and_saveexec_b64 s[14:15], s[38:39]
	global_store_dword v211, v214, s[92:93]
	s_or_b64 exec, exec, s[14:15]
	s_lshl_b32 s94, s51, 8
	s_add_i32 s94, s94, 32
	s_lshl_b32 s94, s94, 14
	s_add_u32 s84, s48, s94
	s_addc_u32 s85, s49, 0
	global_load_dwordx4 v[144:147], v193, s[84:85]
	global_load_dwordx4 v[140:143], v206, s[84:85]
	global_load_dwordx4 v[136:139], v193, s[84:85] offset:512
	global_load_dwordx4 v[132:135], v206, s[84:85] offset:512
	v_mov_b32_dpp v164, v124 row_ror:8 row_mask:0xf bank_mask:0xf
	v_mov_b32_dpp v165, v125 row_ror:8 row_mask:0xf bank_mask:0xf
	v_mov_b32_dpp v166, v126 row_ror:8 row_mask:0xf bank_mask:0xf
	v_mov_b32_dpp v167, v127 row_ror:8 row_mask:0xf bank_mask:0xf
	v_cndmask_b32_e64 v124, v164, v128, s[90:91]
	v_cndmask_b32_e64 v125, v165, v129, s[90:91]
	v_cndmask_b32_e64 v126, v166, v130, s[90:91]
	v_cndmask_b32_e64 v127, v167, v131, s[90:91]
	v_cndmask_b32_e64 v128, v128, v164, s[90:91]
	v_cndmask_b32_e64 v129, v129, v165, s[90:91]
	v_cndmask_b32_e64 v130, v130, v166, s[90:91]
	v_cndmask_b32_e64 v131, v131, v167, s[90:91]
	v_mov_b32_dpp v164, v116 row_ror:8 row_mask:0xf bank_mask:0xf
	v_mov_b32_dpp v165, v117 row_ror:8 row_mask:0xf bank_mask:0xf
	v_mov_b32_dpp v166, v118 row_ror:8 row_mask:0xf bank_mask:0xf
	v_mov_b32_dpp v167, v119 row_ror:8 row_mask:0xf bank_mask:0xf
	v_cndmask_b32_e64 v116, v164, v120, s[90:91]
	v_cndmask_b32_e64 v117, v165, v121, s[90:91]
	v_cndmask_b32_e64 v118, v166, v122, s[90:91]
	v_cndmask_b32_e64 v119, v167, v123, s[90:91]
	v_cndmask_b32_e64 v120, v120, v164, s[90:91]
	v_cndmask_b32_e64 v121, v121, v165, s[90:91]
	v_cndmask_b32_e64 v122, v122, v166, s[90:91]
	v_cndmask_b32_e64 v123, v123, v167, s[90:91]
	s_lshl_b32 s94, s51, 8
	s_add_i32 s94, s94, 16
	s_lshl_b32 s94, s94, 14
	s_add_u32 s86, s48, s94
	s_addc_u32 s87, s49, 0
	s_lshl_b32 s94, s51, 8
	s_add_i32 s94, s94, 16
	s_lshl_b32 s94, s94, 13
	s_add_u32 s88, s12, s94
	s_addc_u32 s89, s13, 0
	s_lshl_b32 s94, s51, 8
	s_add_i32 s94, s94, 16
	s_lshl_b32 s94, s94, 8
	s_add_u32 s92, s22, s94
	s_addc_u32 s93, s23, 0
	s_waitcnt vmcnt(13)
	v_pk_add_f32 v[128:129], v[128:129], v[172:173]
	v_pk_add_f32 v[130:131], v[130:131], v[174:175]
	v_pk_add_f32 v[124:125], v[124:125], v[176:177]
	v_pk_add_f32 v[126:127], v[126:127], v[178:179]
	global_store_dwordx4 v193, v[128:131], s[86:87]
	global_store_dwordx4 v206, v[124:127], s[86:87]
	v_mul_f32_e32 v214, v128, v128
	v_fmac_f32_e32 v214, v129, v129
	v_fmac_f32_e32 v214, v130, v130
	v_fmac_f32_e32 v214, v131, v131
	v_mul_f32_e32 v215, v124, v124
	v_fmac_f32_e32 v215, v125, v125
	v_fmac_f32_e32 v215, v126, v126
	v_fmac_f32_e32 v215, v127, v127
	v_pk_mul_f32 v[164:165], v[128:129], v[148:149]
	v_pk_mul_f32 v[166:167], v[130:131], v[150:151]
	v_cvt_pk_bf16_f32 v168, v164, v165
	v_cvt_pk_bf16_f32 v169, v166, v167
	global_store_dwordx2 v207, v[168:169], s[88:89]
	v_pk_mul_f32 v[164:165], v[124:125], v[156:157]
	v_pk_mul_f32 v[166:167], v[126:127], v[158:159]
	v_cvt_pk_bf16_f32 v170, v164, v165
	v_cvt_pk_bf16_f32 v171, v166, v167
	global_store_dwordx2 v208, v[170:171], s[88:89]
	v_pk_add_f32 v[120:121], v[120:121], v[182:183]
	v_pk_add_f32 v[122:123], v[122:123], v[184:185]
	v_pk_add_f32 v[116:117], v[116:117], v[232:233]
	v_pk_add_f32 v[118:119], v[118:119], v[234:235]
	global_store_dwordx4 v193, v[120:123], s[86:87] offset:512
	global_store_dwordx4 v206, v[116:119], s[86:87] offset:512
	v_fmac_f32_e32 v214, v120, v120
	v_fmac_f32_e32 v214, v121, v121
	v_fmac_f32_e32 v214, v122, v122
	v_fmac_f32_e32 v214, v123, v123
	v_fmac_f32_e32 v215, v116, v116
	v_fmac_f32_e32 v215, v117, v117
	v_fmac_f32_e32 v215, v118, v118
	v_fmac_f32_e32 v215, v119, v119
	v_pk_mul_f32 v[164:165], v[120:121], v[152:153]
	v_pk_mul_f32 v[166:167], v[122:123], v[154:155]
	v_cvt_pk_bf16_f32 v168, v164, v165
	v_cvt_pk_bf16_f32 v169, v166, v167
	global_store_dwordx2 v207, v[168:169], s[88:89] offset:256
	v_pk_mul_f32 v[164:165], v[116:117], v[160:161]
	v_pk_mul_f32 v[166:167], v[118:119], v[162:163]
	v_cvt_pk_bf16_f32 v170, v164, v165
	v_cvt_pk_bf16_f32 v171, v166, v167
	global_store_dwordx2 v208, v[170:171], s[88:89] offset:256
	s_nop 1
	v_add_f32_dpp v180, v214, v214 row_ror:8 row_mask:0xf bank_mask:0xf
	v_add_f32_dpp v192, v215, v215 row_ror:8 row_mask:0xf bank_mask:0xf
	v_cndmask_b32_e64 v214, v180, v192, s[90:91]
	ds_bpermute_b32 v215, v212, v214
	s_waitcnt lgkmcnt(0)
	v_add_f32_e32 v214, v214, v215
	ds_bpermute_b32 v215, v213, v214
	s_waitcnt lgkmcnt(0)
	v_add_f32_e32 v214, v214, v215
	s_and_saveexec_b64 s[14:15], s[38:39]
	global_store_dword v211, v214, s[92:93]
	s_or_b64 exec, exec, s[14:15]
	s_lshl_b32 s94, s51, 8
	s_add_i32 s94, s94, 48
	s_lshl_b32 s94, s94, 14
	s_add_u32 s84, s48, s94
	s_addc_u32 s85, s49, 0
	global_load_dwordx4 v[128:131], v193, s[84:85]
	global_load_dwordx4 v[124:127], v206, s[84:85]
	global_load_dwordx4 v[120:123], v193, s[84:85] offset:512
	global_load_dwordx4 v[116:119], v206, s[84:85] offset:512
	v_mov_b32_dpp v164, v108 row_ror:8 row_mask:0xf bank_mask:0xf
	v_mov_b32_dpp v165, v109 row_ror:8 row_mask:0xf bank_mask:0xf
	v_mov_b32_dpp v166, v110 row_ror:8 row_mask:0xf bank_mask:0xf
	v_mov_b32_dpp v167, v111 row_ror:8 row_mask:0xf bank_mask:0xf
	v_cndmask_b32_e64 v108, v164, v112, s[90:91]
	v_cndmask_b32_e64 v109, v165, v113, s[90:91]
	v_cndmask_b32_e64 v110, v166, v114, s[90:91]
	v_cndmask_b32_e64 v111, v167, v115, s[90:91]
	v_cndmask_b32_e64 v112, v112, v164, s[90:91]
	v_cndmask_b32_e64 v113, v113, v165, s[90:91]
	v_cndmask_b32_e64 v114, v114, v166, s[90:91]
	v_cndmask_b32_e64 v115, v115, v167, s[90:91]
	v_mov_b32_dpp v164, v100 row_ror:8 row_mask:0xf bank_mask:0xf
	v_mov_b32_dpp v165, v101 row_ror:8 row_mask:0xf bank_mask:0xf
	v_mov_b32_dpp v166, v102 row_ror:8 row_mask:0xf bank_mask:0xf
	v_mov_b32_dpp v167, v103 row_ror:8 row_mask:0xf bank_mask:0xf
	v_cndmask_b32_e64 v100, v164, v104, s[90:91]
	v_cndmask_b32_e64 v101, v165, v105, s[90:91]
	v_cndmask_b32_e64 v102, v166, v106, s[90:91]
	v_cndmask_b32_e64 v103, v167, v107, s[90:91]
	v_cndmask_b32_e64 v104, v104, v164, s[90:91]
	v_cndmask_b32_e64 v105, v105, v165, s[90:91]
	v_cndmask_b32_e64 v106, v106, v166, s[90:91]
	v_cndmask_b32_e64 v107, v107, v167, s[90:91]
	s_lshl_b32 s94, s51, 8
	s_add_i32 s94, s94, 32
	s_lshl_b32 s94, s94, 14
	s_add_u32 s86, s48, s94
	s_addc_u32 s87, s49, 0
	s_lshl_b32 s94, s51, 8
	s_add_i32 s94, s94, 32
	s_lshl_b32 s94, s94, 13
	s_add_u32 s88, s12, s94
	s_addc_u32 s89, s13, 0
	s_lshl_b32 s94, s51, 8
	s_add_i32 s94, s94, 32
	s_lshl_b32 s94, s94, 8
	s_add_u32 s92, s22, s94
	s_addc_u32 s93, s23, 0
	s_waitcnt vmcnt(13)
	v_pk_add_f32 v[112:113], v[112:113], v[144:145]
	v_pk_add_f32 v[114:115], v[114:115], v[146:147]
	v_pk_add_f32 v[108:109], v[108:109], v[140:141]
	v_pk_add_f32 v[110:111], v[110:111], v[142:143]
	global_store_dwordx4 v193, v[112:115], s[86:87]
	global_store_dwordx4 v206, v[108:111], s[86:87]
	v_mul_f32_e32 v214, v112, v112
	v_fmac_f32_e32 v214, v113, v113
	v_fmac_f32_e32 v214, v114, v114
	v_fmac_f32_e32 v214, v115, v115
	v_mul_f32_e32 v215, v108, v108
	v_fmac_f32_e32 v215, v109, v109
	v_fmac_f32_e32 v215, v110, v110
	v_fmac_f32_e32 v215, v111, v111
	v_pk_mul_f32 v[164:165], v[112:113], v[148:149]
	v_pk_mul_f32 v[166:167], v[114:115], v[150:151]
	v_cvt_pk_bf16_f32 v168, v164, v165
	v_cvt_pk_bf16_f32 v169, v166, v167
	global_store_dwordx2 v207, v[168:169], s[88:89]
	v_pk_mul_f32 v[164:165], v[108:109], v[156:157]
	v_pk_mul_f32 v[166:167], v[110:111], v[158:159]
	v_cvt_pk_bf16_f32 v170, v164, v165
	v_cvt_pk_bf16_f32 v171, v166, v167
	global_store_dwordx2 v208, v[170:171], s[88:89]
	v_pk_add_f32 v[104:105], v[104:105], v[136:137]
	v_pk_add_f32 v[106:107], v[106:107], v[138:139]
	v_pk_add_f32 v[100:101], v[100:101], v[132:133]
	v_pk_add_f32 v[102:103], v[102:103], v[134:135]
	global_store_dwordx4 v193, v[104:107], s[86:87] offset:512
	global_store_dwordx4 v206, v[100:103], s[86:87] offset:512
	v_fmac_f32_e32 v214, v104, v104
	v_fmac_f32_e32 v214, v105, v105
	v_fmac_f32_e32 v214, v106, v106
	v_fmac_f32_e32 v214, v107, v107
	v_fmac_f32_e32 v215, v100, v100
	v_fmac_f32_e32 v215, v101, v101
	v_fmac_f32_e32 v215, v102, v102
	v_fmac_f32_e32 v215, v103, v103
	v_pk_mul_f32 v[164:165], v[104:105], v[152:153]
	v_pk_mul_f32 v[166:167], v[106:107], v[154:155]
	v_cvt_pk_bf16_f32 v168, v164, v165
	v_cvt_pk_bf16_f32 v169, v166, v167
	global_store_dwordx2 v207, v[168:169], s[88:89] offset:256
	v_pk_mul_f32 v[164:165], v[100:101], v[160:161]
	v_pk_mul_f32 v[166:167], v[102:103], v[162:163]
	v_cvt_pk_bf16_f32 v170, v164, v165
	v_cvt_pk_bf16_f32 v171, v166, v167
	global_store_dwordx2 v208, v[170:171], s[88:89] offset:256
	s_nop 1
	v_add_f32_dpp v180, v214, v214 row_ror:8 row_mask:0xf bank_mask:0xf
	v_add_f32_dpp v192, v215, v215 row_ror:8 row_mask:0xf bank_mask:0xf
	v_cndmask_b32_e64 v214, v180, v192, s[90:91]
	ds_bpermute_b32 v215, v212, v214
	s_waitcnt lgkmcnt(0)
	v_add_f32_e32 v214, v214, v215
	ds_bpermute_b32 v215, v213, v214
	s_waitcnt lgkmcnt(0)
	v_add_f32_e32 v214, v214, v215
	s_and_saveexec_b64 s[14:15], s[38:39]
	global_store_dword v211, v214, s[92:93]
	s_or_b64 exec, exec, s[14:15]
	s_lshl_b32 s94, s51, 8
	s_add_i32 s94, s94, 128
	s_lshl_b32 s94, s94, 14
	s_add_u32 s84, s48, s94
	s_addc_u32 s85, s49, 0
	global_load_dwordx4 v[112:115], v193, s[84:85]
	global_load_dwordx4 v[108:111], v206, s[84:85]
	global_load_dwordx4 v[104:107], v193, s[84:85] offset:512
	global_load_dwordx4 v[100:103], v206, s[84:85] offset:512
	v_mov_b32_dpp v164, v92 row_ror:8 row_mask:0xf bank_mask:0xf
	v_mov_b32_dpp v165, v93 row_ror:8 row_mask:0xf bank_mask:0xf
	v_mov_b32_dpp v166, v94 row_ror:8 row_mask:0xf bank_mask:0xf
	v_mov_b32_dpp v167, v95 row_ror:8 row_mask:0xf bank_mask:0xf
	v_cndmask_b32_e64 v92, v164, v96, s[90:91]
	v_cndmask_b32_e64 v93, v165, v97, s[90:91]
	v_cndmask_b32_e64 v94, v166, v98, s[90:91]
	v_cndmask_b32_e64 v95, v167, v99, s[90:91]
	v_cndmask_b32_e64 v96, v96, v164, s[90:91]
	v_cndmask_b32_e64 v97, v97, v165, s[90:91]
	v_cndmask_b32_e64 v98, v98, v166, s[90:91]
	v_cndmask_b32_e64 v99, v99, v167, s[90:91]
	v_mov_b32_dpp v164, v84 row_ror:8 row_mask:0xf bank_mask:0xf
	v_mov_b32_dpp v165, v85 row_ror:8 row_mask:0xf bank_mask:0xf
	v_mov_b32_dpp v166, v86 row_ror:8 row_mask:0xf bank_mask:0xf
	v_mov_b32_dpp v167, v87 row_ror:8 row_mask:0xf bank_mask:0xf
	v_cndmask_b32_e64 v84, v164, v88, s[90:91]
	v_cndmask_b32_e64 v85, v165, v89, s[90:91]
	v_cndmask_b32_e64 v86, v166, v90, s[90:91]
	v_cndmask_b32_e64 v87, v167, v91, s[90:91]
	v_cndmask_b32_e64 v88, v88, v164, s[90:91]
	v_cndmask_b32_e64 v89, v89, v165, s[90:91]
	v_cndmask_b32_e64 v90, v90, v166, s[90:91]
	v_cndmask_b32_e64 v91, v91, v167, s[90:91]
	s_lshl_b32 s94, s51, 8
	s_add_i32 s94, s94, 48
	s_lshl_b32 s94, s94, 14
	s_add_u32 s86, s48, s94
	s_addc_u32 s87, s49, 0
	s_lshl_b32 s94, s51, 8
	s_add_i32 s94, s94, 48
	s_lshl_b32 s94, s94, 13
	s_add_u32 s88, s12, s94
	s_addc_u32 s89, s13, 0
	s_lshl_b32 s94, s51, 8
	s_add_i32 s94, s94, 48
	s_lshl_b32 s94, s94, 8
	s_add_u32 s92, s22, s94
	s_addc_u32 s93, s23, 0
	s_waitcnt vmcnt(13)
	v_pk_add_f32 v[96:97], v[96:97], v[128:129]
	v_pk_add_f32 v[98:99], v[98:99], v[130:131]
	v_pk_add_f32 v[92:93], v[92:93], v[124:125]
	v_pk_add_f32 v[94:95], v[94:95], v[126:127]
	global_store_dwordx4 v193, v[96:99], s[86:87]
	global_store_dwordx4 v206, v[92:95], s[86:87]
	v_mul_f32_e32 v214, v96, v96
	v_fmac_f32_e32 v214, v97, v97
	v_fmac_f32_e32 v214, v98, v98
	v_fmac_f32_e32 v214, v99, v99
	v_mul_f32_e32 v215, v92, v92
	v_fmac_f32_e32 v215, v93, v93
	v_fmac_f32_e32 v215, v94, v94
	v_fmac_f32_e32 v215, v95, v95
	v_pk_mul_f32 v[164:165], v[96:97], v[148:149]
	v_pk_mul_f32 v[166:167], v[98:99], v[150:151]
	v_cvt_pk_bf16_f32 v168, v164, v165
	v_cvt_pk_bf16_f32 v169, v166, v167
	global_store_dwordx2 v207, v[168:169], s[88:89]
	v_pk_mul_f32 v[164:165], v[92:93], v[156:157]
	v_pk_mul_f32 v[166:167], v[94:95], v[158:159]
	v_cvt_pk_bf16_f32 v170, v164, v165
	v_cvt_pk_bf16_f32 v171, v166, v167
	global_store_dwordx2 v208, v[170:171], s[88:89]
	v_pk_add_f32 v[88:89], v[88:89], v[120:121]
	v_pk_add_f32 v[90:91], v[90:91], v[122:123]
	v_pk_add_f32 v[84:85], v[84:85], v[116:117]
	v_pk_add_f32 v[86:87], v[86:87], v[118:119]
	global_store_dwordx4 v193, v[88:91], s[86:87] offset:512
	global_store_dwordx4 v206, v[84:87], s[86:87] offset:512
	v_fmac_f32_e32 v214, v88, v88
	v_fmac_f32_e32 v214, v89, v89
	v_fmac_f32_e32 v214, v90, v90
	v_fmac_f32_e32 v214, v91, v91
	v_fmac_f32_e32 v215, v84, v84
	v_fmac_f32_e32 v215, v85, v85
	v_fmac_f32_e32 v215, v86, v86
	v_fmac_f32_e32 v215, v87, v87
	v_pk_mul_f32 v[164:165], v[88:89], v[152:153]
	v_pk_mul_f32 v[166:167], v[90:91], v[154:155]
	v_cvt_pk_bf16_f32 v168, v164, v165
	v_cvt_pk_bf16_f32 v169, v166, v167
	global_store_dwordx2 v207, v[168:169], s[88:89] offset:256
	v_pk_mul_f32 v[164:165], v[84:85], v[160:161]
	v_pk_mul_f32 v[166:167], v[86:87], v[162:163]
	v_cvt_pk_bf16_f32 v170, v164, v165
	v_cvt_pk_bf16_f32 v171, v166, v167
	global_store_dwordx2 v208, v[170:171], s[88:89] offset:256
	s_nop 1
	v_add_f32_dpp v180, v214, v214 row_ror:8 row_mask:0xf bank_mask:0xf
	v_add_f32_dpp v192, v215, v215 row_ror:8 row_mask:0xf bank_mask:0xf
	v_cndmask_b32_e64 v214, v180, v192, s[90:91]
	ds_bpermute_b32 v215, v212, v214
	s_waitcnt lgkmcnt(0)
	v_add_f32_e32 v214, v214, v215
	ds_bpermute_b32 v215, v213, v214
	s_waitcnt lgkmcnt(0)
	v_add_f32_e32 v214, v214, v215
	s_and_saveexec_b64 s[14:15], s[38:39]
	global_store_dword v211, v214, s[92:93]
	s_or_b64 exec, exec, s[14:15]
	s_lshl_b32 s94, s51, 8
	s_add_i32 s94, s94, 144
	s_lshl_b32 s94, s94, 14
	s_add_u32 s84, s48, s94
	s_addc_u32 s85, s49, 0
	global_load_dwordx4 v[96:99], v193, s[84:85]
	global_load_dwordx4 v[92:95], v206, s[84:85]
	global_load_dwordx4 v[88:91], v193, s[84:85] offset:512
	global_load_dwordx4 v[84:87], v206, s[84:85] offset:512
	v_mov_b32_dpp v164, v64 row_ror:8 row_mask:0xf bank_mask:0xf
	v_mov_b32_dpp v165, v65 row_ror:8 row_mask:0xf bank_mask:0xf
	v_mov_b32_dpp v166, v66 row_ror:8 row_mask:0xf bank_mask:0xf
	v_mov_b32_dpp v167, v67 row_ror:8 row_mask:0xf bank_mask:0xf
	v_cndmask_b32_e64 v64, v164, v72, s[90:91]
	v_cndmask_b32_e64 v65, v165, v73, s[90:91]
	v_cndmask_b32_e64 v66, v166, v74, s[90:91]
	v_cndmask_b32_e64 v67, v167, v75, s[90:91]
	v_cndmask_b32_e64 v72, v72, v164, s[90:91]
	v_cndmask_b32_e64 v73, v73, v165, s[90:91]
	v_cndmask_b32_e64 v74, v74, v166, s[90:91]
	v_cndmask_b32_e64 v75, v75, v167, s[90:91]
	v_mov_b32_dpp v164, v52 row_ror:8 row_mask:0xf bank_mask:0xf
	v_mov_b32_dpp v165, v53 row_ror:8 row_mask:0xf bank_mask:0xf
	v_mov_b32_dpp v166, v54 row_ror:8 row_mask:0xf bank_mask:0xf
	v_mov_b32_dpp v167, v55 row_ror:8 row_mask:0xf bank_mask:0xf
	v_cndmask_b32_e64 v52, v164, v56, s[90:91]
	v_cndmask_b32_e64 v53, v165, v57, s[90:91]
	v_cndmask_b32_e64 v54, v166, v58, s[90:91]
	v_cndmask_b32_e64 v55, v167, v59, s[90:91]
	v_cndmask_b32_e64 v56, v56, v164, s[90:91]
	v_cndmask_b32_e64 v57, v57, v165, s[90:91]
	v_cndmask_b32_e64 v58, v58, v166, s[90:91]
	v_cndmask_b32_e64 v59, v59, v167, s[90:91]
	s_lshl_b32 s94, s51, 8
	s_add_i32 s94, s94, 128
	s_lshl_b32 s94, s94, 14
	s_add_u32 s86, s48, s94
	s_addc_u32 s87, s49, 0
	s_lshl_b32 s94, s51, 8
	s_add_i32 s94, s94, 128
	s_lshl_b32 s94, s94, 13
	s_add_u32 s88, s12, s94
	s_addc_u32 s89, s13, 0
	s_lshl_b32 s94, s51, 8
	s_add_i32 s94, s94, 128
	s_lshl_b32 s94, s94, 8
	s_add_u32 s92, s22, s94
	s_addc_u32 s93, s23, 0
	s_waitcnt vmcnt(13)
	v_pk_add_f32 v[72:73], v[72:73], v[112:113]
	v_pk_add_f32 v[74:75], v[74:75], v[114:115]
	v_pk_add_f32 v[64:65], v[64:65], v[108:109]
	v_pk_add_f32 v[66:67], v[66:67], v[110:111]
	global_store_dwordx4 v193, v[72:75], s[86:87]
	global_store_dwordx4 v206, v[64:67], s[86:87]
	v_mul_f32_e32 v214, v72, v72
	v_fmac_f32_e32 v214, v73, v73
	v_fmac_f32_e32 v214, v74, v74
	v_fmac_f32_e32 v214, v75, v75
	v_mul_f32_e32 v215, v64, v64
	v_fmac_f32_e32 v215, v65, v65
	v_fmac_f32_e32 v215, v66, v66
	v_fmac_f32_e32 v215, v67, v67
	v_pk_mul_f32 v[164:165], v[72:73], v[148:149]
	v_pk_mul_f32 v[166:167], v[74:75], v[150:151]
	v_cvt_pk_bf16_f32 v168, v164, v165
	v_cvt_pk_bf16_f32 v169, v166, v167
	global_store_dwordx2 v207, v[168:169], s[88:89]
	v_pk_mul_f32 v[164:165], v[64:65], v[156:157]
	v_pk_mul_f32 v[166:167], v[66:67], v[158:159]
	v_cvt_pk_bf16_f32 v170, v164, v165
	v_cvt_pk_bf16_f32 v171, v166, v167
	global_store_dwordx2 v208, v[170:171], s[88:89]
	v_pk_add_f32 v[56:57], v[56:57], v[104:105]
	v_pk_add_f32 v[58:59], v[58:59], v[106:107]
	v_pk_add_f32 v[52:53], v[52:53], v[100:101]
	v_pk_add_f32 v[54:55], v[54:55], v[102:103]
	global_store_dwordx4 v193, v[56:59], s[86:87] offset:512
	global_store_dwordx4 v206, v[52:55], s[86:87] offset:512
	v_fmac_f32_e32 v214, v56, v56
	v_fmac_f32_e32 v214, v57, v57
	v_fmac_f32_e32 v214, v58, v58
	v_fmac_f32_e32 v214, v59, v59
	v_fmac_f32_e32 v215, v52, v52
	v_fmac_f32_e32 v215, v53, v53
	v_fmac_f32_e32 v215, v54, v54
	v_fmac_f32_e32 v215, v55, v55
	v_pk_mul_f32 v[164:165], v[56:57], v[152:153]
	v_pk_mul_f32 v[166:167], v[58:59], v[154:155]
	v_cvt_pk_bf16_f32 v168, v164, v165
	v_cvt_pk_bf16_f32 v169, v166, v167
	global_store_dwordx2 v207, v[168:169], s[88:89] offset:256
	v_pk_mul_f32 v[164:165], v[52:53], v[160:161]
	v_pk_mul_f32 v[166:167], v[54:55], v[162:163]
	v_cvt_pk_bf16_f32 v170, v164, v165
	v_cvt_pk_bf16_f32 v171, v166, v167
	global_store_dwordx2 v208, v[170:171], s[88:89] offset:256
	s_nop 1
	v_add_f32_dpp v180, v214, v214 row_ror:8 row_mask:0xf bank_mask:0xf
	v_add_f32_dpp v192, v215, v215 row_ror:8 row_mask:0xf bank_mask:0xf
	v_cndmask_b32_e64 v214, v180, v192, s[90:91]
	ds_bpermute_b32 v215, v212, v214
	s_waitcnt lgkmcnt(0)
	v_add_f32_e32 v214, v214, v215
	ds_bpermute_b32 v215, v213, v214
	s_waitcnt lgkmcnt(0)
	v_add_f32_e32 v214, v214, v215
	s_and_saveexec_b64 s[14:15], s[38:39]
	global_store_dword v211, v214, s[92:93]
	s_or_b64 exec, exec, s[14:15]
	s_lshl_b32 s94, s51, 8
	s_add_i32 s94, s94, 160
	s_lshl_b32 s94, s94, 14
	s_add_u32 s84, s48, s94
	s_addc_u32 s85, s49, 0
	global_load_dwordx4 v[72:75], v193, s[84:85]
	global_load_dwordx4 v[64:67], v206, s[84:85]
	global_load_dwordx4 v[56:59], v193, s[84:85] offset:512
	global_load_dwordx4 v[52:55], v206, s[84:85] offset:512
	v_mov_b32_dpp v164, v44 row_ror:8 row_mask:0xf bank_mask:0xf
	v_mov_b32_dpp v165, v45 row_ror:8 row_mask:0xf bank_mask:0xf
	v_mov_b32_dpp v166, v46 row_ror:8 row_mask:0xf bank_mask:0xf
	v_mov_b32_dpp v167, v47 row_ror:8 row_mask:0xf bank_mask:0xf
	v_cndmask_b32_e64 v44, v164, v48, s[90:91]
	v_cndmask_b32_e64 v45, v165, v49, s[90:91]
	v_cndmask_b32_e64 v46, v166, v50, s[90:91]
	v_cndmask_b32_e64 v47, v167, v51, s[90:91]
	v_cndmask_b32_e64 v48, v48, v164, s[90:91]
	v_cndmask_b32_e64 v49, v49, v165, s[90:91]
	v_cndmask_b32_e64 v50, v50, v166, s[90:91]
	v_cndmask_b32_e64 v51, v51, v167, s[90:91]
	v_mov_b32_dpp v164, v36 row_ror:8 row_mask:0xf bank_mask:0xf
	v_mov_b32_dpp v165, v37 row_ror:8 row_mask:0xf bank_mask:0xf
	v_mov_b32_dpp v166, v38 row_ror:8 row_mask:0xf bank_mask:0xf
	v_mov_b32_dpp v167, v39 row_ror:8 row_mask:0xf bank_mask:0xf
	v_cndmask_b32_e64 v36, v164, v40, s[90:91]
	v_cndmask_b32_e64 v37, v165, v41, s[90:91]
	v_cndmask_b32_e64 v38, v166, v42, s[90:91]
	v_cndmask_b32_e64 v39, v167, v43, s[90:91]
	v_cndmask_b32_e64 v40, v40, v164, s[90:91]
	v_cndmask_b32_e64 v41, v41, v165, s[90:91]
	v_cndmask_b32_e64 v42, v42, v166, s[90:91]
	v_cndmask_b32_e64 v43, v43, v167, s[90:91]
	s_lshl_b32 s94, s51, 8
	s_add_i32 s94, s94, 144
	s_lshl_b32 s94, s94, 14
	s_add_u32 s86, s48, s94
	s_addc_u32 s87, s49, 0
	s_lshl_b32 s94, s51, 8
	s_add_i32 s94, s94, 144
	s_lshl_b32 s94, s94, 13
	s_add_u32 s88, s12, s94
	s_addc_u32 s89, s13, 0
	s_lshl_b32 s94, s51, 8
	s_add_i32 s94, s94, 144
	s_lshl_b32 s94, s94, 8
	s_add_u32 s92, s22, s94
	s_addc_u32 s93, s23, 0
	s_waitcnt vmcnt(13)
	v_pk_add_f32 v[48:49], v[48:49], v[96:97]
	v_pk_add_f32 v[50:51], v[50:51], v[98:99]
	v_pk_add_f32 v[44:45], v[44:45], v[92:93]
	v_pk_add_f32 v[46:47], v[46:47], v[94:95]
	global_store_dwordx4 v193, v[48:51], s[86:87]
	global_store_dwordx4 v206, v[44:47], s[86:87]
	v_mul_f32_e32 v214, v48, v48
	v_fmac_f32_e32 v214, v49, v49
	v_fmac_f32_e32 v214, v50, v50
	v_fmac_f32_e32 v214, v51, v51
	v_mul_f32_e32 v215, v44, v44
	v_fmac_f32_e32 v215, v45, v45
	v_fmac_f32_e32 v215, v46, v46
	v_fmac_f32_e32 v215, v47, v47
	v_pk_mul_f32 v[164:165], v[48:49], v[148:149]
	v_pk_mul_f32 v[166:167], v[50:51], v[150:151]
	v_cvt_pk_bf16_f32 v168, v164, v165
	v_cvt_pk_bf16_f32 v169, v166, v167
	global_store_dwordx2 v207, v[168:169], s[88:89]
	v_pk_mul_f32 v[164:165], v[44:45], v[156:157]
	v_pk_mul_f32 v[166:167], v[46:47], v[158:159]
	v_cvt_pk_bf16_f32 v170, v164, v165
	v_cvt_pk_bf16_f32 v171, v166, v167
	global_store_dwordx2 v208, v[170:171], s[88:89]
	v_pk_add_f32 v[40:41], v[40:41], v[88:89]
	v_pk_add_f32 v[42:43], v[42:43], v[90:91]
	v_pk_add_f32 v[36:37], v[36:37], v[84:85]
	v_pk_add_f32 v[38:39], v[38:39], v[86:87]
	global_store_dwordx4 v193, v[40:43], s[86:87] offset:512
	global_store_dwordx4 v206, v[36:39], s[86:87] offset:512
	v_fmac_f32_e32 v214, v40, v40
	v_fmac_f32_e32 v214, v41, v41
	v_fmac_f32_e32 v214, v42, v42
	v_fmac_f32_e32 v214, v43, v43
	v_fmac_f32_e32 v215, v36, v36
	v_fmac_f32_e32 v215, v37, v37
	v_fmac_f32_e32 v215, v38, v38
	v_fmac_f32_e32 v215, v39, v39
	v_pk_mul_f32 v[164:165], v[40:41], v[152:153]
	v_pk_mul_f32 v[166:167], v[42:43], v[154:155]
	v_cvt_pk_bf16_f32 v168, v164, v165
	v_cvt_pk_bf16_f32 v169, v166, v167
	global_store_dwordx2 v207, v[168:169], s[88:89] offset:256
	v_pk_mul_f32 v[164:165], v[36:37], v[160:161]
	v_pk_mul_f32 v[166:167], v[38:39], v[162:163]
	v_cvt_pk_bf16_f32 v170, v164, v165
	v_cvt_pk_bf16_f32 v171, v166, v167
	global_store_dwordx2 v208, v[170:171], s[88:89] offset:256
	s_nop 1
	v_add_f32_dpp v180, v214, v214 row_ror:8 row_mask:0xf bank_mask:0xf
	v_add_f32_dpp v192, v215, v215 row_ror:8 row_mask:0xf bank_mask:0xf
	v_cndmask_b32_e64 v214, v180, v192, s[90:91]
	ds_bpermute_b32 v215, v212, v214
	s_waitcnt lgkmcnt(0)
	v_add_f32_e32 v214, v214, v215
	ds_bpermute_b32 v215, v213, v214
	s_waitcnt lgkmcnt(0)
	v_add_f32_e32 v214, v214, v215
	s_and_saveexec_b64 s[14:15], s[38:39]
	global_store_dword v211, v214, s[92:93]
	s_or_b64 exec, exec, s[14:15]
	s_lshl_b32 s94, s51, 8
	s_add_i32 s94, s94, 176
	s_lshl_b32 s94, s94, 14
	s_add_u32 s84, s48, s94
	s_addc_u32 s85, s49, 0
	global_load_dwordx4 v[48:51], v193, s[84:85]
	global_load_dwordx4 v[44:47], v206, s[84:85]
	global_load_dwordx4 v[40:43], v193, s[84:85] offset:512
	global_load_dwordx4 v[36:39], v206, s[84:85] offset:512
	v_mov_b32_dpp v164, v28 row_ror:8 row_mask:0xf bank_mask:0xf
	v_mov_b32_dpp v165, v29 row_ror:8 row_mask:0xf bank_mask:0xf
	v_mov_b32_dpp v166, v30 row_ror:8 row_mask:0xf bank_mask:0xf
	v_mov_b32_dpp v167, v31 row_ror:8 row_mask:0xf bank_mask:0xf
	v_cndmask_b32_e64 v28, v164, v32, s[90:91]
	v_cndmask_b32_e64 v29, v165, v33, s[90:91]
	v_cndmask_b32_e64 v30, v166, v34, s[90:91]
	v_cndmask_b32_e64 v31, v167, v35, s[90:91]
	v_cndmask_b32_e64 v32, v32, v164, s[90:91]
	v_cndmask_b32_e64 v33, v33, v165, s[90:91]
	v_cndmask_b32_e64 v34, v34, v166, s[90:91]
	v_cndmask_b32_e64 v35, v35, v167, s[90:91]
	v_mov_b32_dpp v164, v20 row_ror:8 row_mask:0xf bank_mask:0xf
	v_mov_b32_dpp v165, v21 row_ror:8 row_mask:0xf bank_mask:0xf
	v_mov_b32_dpp v166, v22 row_ror:8 row_mask:0xf bank_mask:0xf
	v_mov_b32_dpp v167, v23 row_ror:8 row_mask:0xf bank_mask:0xf
	v_cndmask_b32_e64 v20, v164, v24, s[90:91]
	v_cndmask_b32_e64 v21, v165, v25, s[90:91]
	v_cndmask_b32_e64 v22, v166, v26, s[90:91]
	v_cndmask_b32_e64 v23, v167, v27, s[90:91]
	v_cndmask_b32_e64 v24, v24, v164, s[90:91]
	v_cndmask_b32_e64 v25, v25, v165, s[90:91]
	v_cndmask_b32_e64 v26, v26, v166, s[90:91]
	v_cndmask_b32_e64 v27, v27, v167, s[90:91]
	s_lshl_b32 s94, s51, 8
	s_add_i32 s94, s94, 160
	s_lshl_b32 s94, s94, 14
	s_add_u32 s86, s48, s94
	s_addc_u32 s87, s49, 0
	s_lshl_b32 s94, s51, 8
	s_add_i32 s94, s94, 160
	s_lshl_b32 s94, s94, 13
	s_add_u32 s88, s12, s94
	s_addc_u32 s89, s13, 0
	s_lshl_b32 s94, s51, 8
	s_add_i32 s94, s94, 160
	s_lshl_b32 s94, s94, 8
	s_add_u32 s92, s22, s94
	s_addc_u32 s93, s23, 0
	s_waitcnt vmcnt(13)
	v_pk_add_f32 v[32:33], v[32:33], v[72:73]
	v_pk_add_f32 v[34:35], v[34:35], v[74:75]
	v_pk_add_f32 v[28:29], v[28:29], v[64:65]
	v_pk_add_f32 v[30:31], v[30:31], v[66:67]
	global_store_dwordx4 v193, v[32:35], s[86:87]
	global_store_dwordx4 v206, v[28:31], s[86:87]
	v_mul_f32_e32 v214, v32, v32
	v_fmac_f32_e32 v214, v33, v33
	v_fmac_f32_e32 v214, v34, v34
	v_fmac_f32_e32 v214, v35, v35
	v_mul_f32_e32 v215, v28, v28
	v_fmac_f32_e32 v215, v29, v29
	v_fmac_f32_e32 v215, v30, v30
	v_fmac_f32_e32 v215, v31, v31
	v_pk_mul_f32 v[164:165], v[32:33], v[148:149]
	v_pk_mul_f32 v[166:167], v[34:35], v[150:151]
	v_cvt_pk_bf16_f32 v168, v164, v165
	v_cvt_pk_bf16_f32 v169, v166, v167
	global_store_dwordx2 v207, v[168:169], s[88:89]
	v_pk_mul_f32 v[164:165], v[28:29], v[156:157]
	v_pk_mul_f32 v[166:167], v[30:31], v[158:159]
	v_cvt_pk_bf16_f32 v170, v164, v165
	v_cvt_pk_bf16_f32 v171, v166, v167
	global_store_dwordx2 v208, v[170:171], s[88:89]
	v_pk_add_f32 v[24:25], v[24:25], v[56:57]
	v_pk_add_f32 v[26:27], v[26:27], v[58:59]
	v_pk_add_f32 v[20:21], v[20:21], v[52:53]
	v_pk_add_f32 v[22:23], v[22:23], v[54:55]
	global_store_dwordx4 v193, v[24:27], s[86:87] offset:512
	global_store_dwordx4 v206, v[20:23], s[86:87] offset:512
	v_fmac_f32_e32 v214, v24, v24
	v_fmac_f32_e32 v214, v25, v25
	v_fmac_f32_e32 v214, v26, v26
	v_fmac_f32_e32 v214, v27, v27
	v_fmac_f32_e32 v215, v20, v20
	v_fmac_f32_e32 v215, v21, v21
	v_fmac_f32_e32 v215, v22, v22
	v_fmac_f32_e32 v215, v23, v23
	v_pk_mul_f32 v[164:165], v[24:25], v[152:153]
	v_pk_mul_f32 v[166:167], v[26:27], v[154:155]
	v_cvt_pk_bf16_f32 v168, v164, v165
	v_cvt_pk_bf16_f32 v169, v166, v167
	global_store_dwordx2 v207, v[168:169], s[88:89] offset:256
	v_pk_mul_f32 v[164:165], v[20:21], v[160:161]
	v_pk_mul_f32 v[166:167], v[22:23], v[162:163]
	v_cvt_pk_bf16_f32 v170, v164, v165
	v_cvt_pk_bf16_f32 v171, v166, v167
	global_store_dwordx2 v208, v[170:171], s[88:89] offset:256
	s_nop 1
	v_add_f32_dpp v180, v214, v214 row_ror:8 row_mask:0xf bank_mask:0xf
	v_add_f32_dpp v192, v215, v215 row_ror:8 row_mask:0xf bank_mask:0xf
	v_cndmask_b32_e64 v214, v180, v192, s[90:91]
	ds_bpermute_b32 v215, v212, v214
	s_waitcnt lgkmcnt(0)
	v_add_f32_e32 v214, v214, v215
	ds_bpermute_b32 v215, v213, v214
	s_waitcnt lgkmcnt(0)
	v_add_f32_e32 v214, v214, v215
	s_and_saveexec_b64 s[14:15], s[38:39]
	global_store_dword v211, v214, s[92:93]
	s_or_b64 exec, exec, s[14:15]
	v_mov_b32_dpp v164, v12 row_ror:8 row_mask:0xf bank_mask:0xf
	v_mov_b32_dpp v165, v13 row_ror:8 row_mask:0xf bank_mask:0xf
	v_mov_b32_dpp v166, v14 row_ror:8 row_mask:0xf bank_mask:0xf
	v_mov_b32_dpp v167, v15 row_ror:8 row_mask:0xf bank_mask:0xf
	v_cndmask_b32_e64 v12, v164, v16, s[90:91]
	v_cndmask_b32_e64 v13, v165, v17, s[90:91]
	v_cndmask_b32_e64 v14, v166, v18, s[90:91]
	v_cndmask_b32_e64 v15, v167, v19, s[90:91]
	v_cndmask_b32_e64 v16, v16, v164, s[90:91]
	v_cndmask_b32_e64 v17, v17, v165, s[90:91]
	v_cndmask_b32_e64 v18, v18, v166, s[90:91]
	v_cndmask_b32_e64 v19, v19, v167, s[90:91]
	v_mov_b32_dpp v164, v4 row_ror:8 row_mask:0xf bank_mask:0xf
	v_mov_b32_dpp v165, v5 row_ror:8 row_mask:0xf bank_mask:0xf
	v_mov_b32_dpp v166, v6 row_ror:8 row_mask:0xf bank_mask:0xf
	v_mov_b32_dpp v167, v7 row_ror:8 row_mask:0xf bank_mask:0xf
	v_cndmask_b32_e64 v4, v164, v8, s[90:91]
	v_cndmask_b32_e64 v5, v165, v9, s[90:91]
	v_cndmask_b32_e64 v6, v166, v10, s[90:91]
	v_cndmask_b32_e64 v7, v167, v11, s[90:91]
	v_cndmask_b32_e64 v8, v8, v164, s[90:91]
	v_cndmask_b32_e64 v9, v9, v165, s[90:91]
	v_cndmask_b32_e64 v10, v10, v166, s[90:91]
	v_cndmask_b32_e64 v11, v11, v167, s[90:91]
	s_lshl_b32 s94, s51, 8
	s_add_i32 s94, s94, 176
	s_lshl_b32 s94, s94, 14
	s_add_u32 s86, s48, s94
	s_addc_u32 s87, s49, 0
	s_lshl_b32 s94, s51, 8
	s_add_i32 s94, s94, 176
	s_lshl_b32 s94, s94, 13
	s_add_u32 s88, s12, s94
	s_addc_u32 s89, s13, 0
	s_lshl_b32 s94, s51, 8
	s_add_i32 s94, s94, 176
	s_lshl_b32 s94, s94, 8
	s_add_u32 s92, s22, s94
	s_addc_u32 s93, s23, 0
	s_waitcnt vmcnt(9)
	v_pk_add_f32 v[16:17], v[16:17], v[48:49]
	v_pk_add_f32 v[18:19], v[18:19], v[50:51]
	v_pk_add_f32 v[12:13], v[12:13], v[44:45]
	v_pk_add_f32 v[14:15], v[14:15], v[46:47]
	global_store_dwordx4 v193, v[16:19], s[86:87]
	global_store_dwordx4 v206, v[12:15], s[86:87]
	v_mul_f32_e32 v214, v16, v16
	v_fmac_f32_e32 v214, v17, v17
	v_fmac_f32_e32 v214, v18, v18
	v_fmac_f32_e32 v214, v19, v19
	v_mul_f32_e32 v215, v12, v12
	v_fmac_f32_e32 v215, v13, v13
	v_fmac_f32_e32 v215, v14, v14
	v_fmac_f32_e32 v215, v15, v15
	v_pk_mul_f32 v[164:165], v[16:17], v[148:149]
	v_pk_mul_f32 v[166:167], v[18:19], v[150:151]
	v_cvt_pk_bf16_f32 v168, v164, v165
	v_cvt_pk_bf16_f32 v169, v166, v167
	global_store_dwordx2 v207, v[168:169], s[88:89]
	v_pk_mul_f32 v[164:165], v[12:13], v[156:157]
	v_pk_mul_f32 v[166:167], v[14:15], v[158:159]
	v_cvt_pk_bf16_f32 v170, v164, v165
	v_cvt_pk_bf16_f32 v171, v166, v167
	global_store_dwordx2 v208, v[170:171], s[88:89]
	v_pk_add_f32 v[8:9], v[8:9], v[40:41]
	v_pk_add_f32 v[10:11], v[10:11], v[42:43]
	v_pk_add_f32 v[4:5], v[4:5], v[36:37]
	v_pk_add_f32 v[6:7], v[6:7], v[38:39]
	global_store_dwordx4 v193, v[8:11], s[86:87] offset:512
	global_store_dwordx4 v206, v[4:7], s[86:87] offset:512
	v_fmac_f32_e32 v214, v8, v8
	v_fmac_f32_e32 v214, v9, v9
	v_fmac_f32_e32 v214, v10, v10
	v_fmac_f32_e32 v214, v11, v11
	v_fmac_f32_e32 v215, v4, v4
	v_fmac_f32_e32 v215, v5, v5
	v_fmac_f32_e32 v215, v6, v6
	v_fmac_f32_e32 v215, v7, v7
	v_pk_mul_f32 v[164:165], v[8:9], v[152:153]
	v_pk_mul_f32 v[166:167], v[10:11], v[154:155]
	v_cvt_pk_bf16_f32 v168, v164, v165
	v_cvt_pk_bf16_f32 v169, v166, v167
	global_store_dwordx2 v207, v[168:169], s[88:89] offset:256
	v_pk_mul_f32 v[164:165], v[4:5], v[160:161]
	v_pk_mul_f32 v[166:167], v[6:7], v[162:163]
	v_cvt_pk_bf16_f32 v170, v164, v165
	v_cvt_pk_bf16_f32 v171, v166, v167
	global_store_dwordx2 v208, v[170:171], s[88:89] offset:256
	s_nop 1
	v_add_f32_dpp v180, v214, v214 row_ror:8 row_mask:0xf bank_mask:0xf
	v_add_f32_dpp v192, v215, v215 row_ror:8 row_mask:0xf bank_mask:0xf
	v_cndmask_b32_e64 v214, v180, v192, s[90:91]
	ds_bpermute_b32 v215, v212, v214
	s_waitcnt lgkmcnt(0)
	v_add_f32_e32 v214, v214, v215
	ds_bpermute_b32 v215, v213, v214
	s_waitcnt lgkmcnt(0)
	v_add_f32_e32 v214, v214, v215
	s_and_saveexec_b64 s[14:15], s[38:39]
	global_store_dword v211, v214, s[92:93]
	s_or_b64 exec, exec, s[14:15]
	s_branch .Lp8epi_end
.Lp8epi_noxg:
	v_and_b32_e32 v192, 8, v219
	v_cmp_ne_u32_e64 s[90:91], 0, v192
	v_sub_u32_e32 v214, v1, v192
	v_lshlrev_b32_e32 v192, 1, v192
	s_lshl_b32 s94, s50, 8
	v_add3_u32 v215, v240, v192, s94
	v_sub_u32_e32 v180, v240, v192
	v_add3_u32 v180, v180, 16, s94
	v_lshlrev_b32_e32 v193, 14, v214
	v_lshl_add_u32 v206, v180, 2, v193
	v_add_u32_e32 v206, 0x20000, v206
	v_lshl_add_u32 v193, v215, 2, v193
	v_lshlrev_b32_e32 v207, 13, v214
	v_lshl_add_u32 v208, v180, 1, v207
	v_add_u32_e32 v208, 0x10000, v208
	v_lshl_add_u32 v207, v215, 1, v207
	v_lshlrev_b32_e32 v209, 2, v215
	v_lshlrev_b32_e32 v210, 2, v180
	s_lshl_b32 s94, s50, 4
	s_lshl_b32 s95, s34, 2
	s_add_i32 s94, s94, s95
	v_lshlrev_b32_e32 v211, 8, v1
	v_add_u32_e32 v211, s94, v211
	v_xor_b32_e32 v212, 16, v219
	v_lshlrev_b32_e32 v212, 2, v212
	v_xor_b32_e32 v213, 32, v219
	v_lshlrev_b32_e32 v213, 2, v213
	s_lshl_b32 s94, s51, 8
	s_lshl_b32 s94, s94, 14
	s_add_u32 s84, s48, s94
	s_addc_u32 s85, s49, 0
	global_load_dwordx4 v[60:63], v193, s[84:85]
	global_load_dwordx4 v[68:71], v206, s[84:85]
	global_load_dwordx4 v[76:79], v193, s[84:85] offset:512
	global_load_dwordx4 v[80:83], v206, s[84:85] offset:512
	s_lshl_b32 s94, s51, 8
	s_add_i32 s94, s94, 16
	s_lshl_b32 s94, s94, 14
	s_add_u32 s84, s48, s94
	s_addc_u32 s85, s49, 0
	global_load_dwordx4 v[172:175], v193, s[84:85]
	global_load_dwordx4 v[176:179], v206, s[84:85]
	global_load_dwordx4 v[182:185], v193, s[84:85] offset:512
	global_load_dwordx4 v[232:235], v206, s[84:85] offset:512
	v_mov_b32_dpp v164, v140 row_ror:8 row_mask:0xf bank_mask:0xf
	v_mov_b32_dpp v165, v141 row_ror:8 row_mask:0xf bank_mask:0xf
	v_mov_b32_dpp v166, v142 row_ror:8 row_mask:0xf bank_mask:0xf
	v_mov_b32_dpp v167, v143 row_ror:8 row_mask:0xf bank_mask:0xf
	v_cndmask_b32_e64 v140, v164, v144, s[90:91]
	v_cndmask_b32_e64 v141, v165, v145, s[90:91]
	v_cndmask_b32_e64 v142, v166, v146, s[90:91]
	v_cndmask_b32_e64 v143, v167, v147, s[90:91]
	v_cndmask_b32_e64 v144, v144, v164, s[90:91]
	v_cndmask_b32_e64 v145, v145, v165, s[90:91]
	v_cndmask_b32_e64 v146, v146, v166, s[90:91]
	v_cndmask_b32_e64 v147, v147, v167, s[90:91]
	v_mov_b32_dpp v164, v132 row_ror:8 row_mask:0xf bank_mask:0xf
	v_mov_b32_dpp v165, v133 row_ror:8 row_mask:0xf bank_mask:0xf
	v_mov_b32_dpp v166, v134 row_ror:8 row_mask:0xf bank_mask:0xf
	v_mov_b32_dpp v167, v135 row_ror:8 row_mask:0xf bank_mask:0xf
	v_cndmask_b32_e64 v132, v164, v136, s[90:91]
	v_cndmask_b32_e64 v133, v165, v137, s[90:91]
	v_cndmask_b32_e64 v134, v166, v138, s[90:91]
	v_cndmask_b32_e64 v135, v167, v139, s[90:91]
	v_cndmask_b32_e64 v136, v136, v164, s[90:91]
	v_cndmask_b32_e64 v137, v137, v165, s[90:91]
	v_cndmask_b32_e64 v138, v138, v166, s[90:91]
	v_cndmask_b32_e64 v139, v139, v167, s[90:91]
	s_lshl_b32 s94, s51, 8
	s_lshl_b32 s94, s94, 14
	s_add_u32 s86, s48, s94
	s_addc_u32 s87, s49, 0
	s_lshl_b32 s94, s51, 8
	s_lshl_b32 s94, s94, 13
	s_add_u32 s88, s12, s94
	s_addc_u32 s89, s13, 0
	s_lshl_b32 s94, s51, 8
	s_lshl_b32 s94, s94, 8
	s_add_u32 s92, s22, s94
	s_addc_u32 s93, s23, 0
	s_waitcnt vmcnt(4)
	v_pk_add_f32 v[144:145], v[144:145], v[60:61]
	v_pk_add_f32 v[146:147], v[146:147], v[62:63]
	v_pk_add_f32 v[140:141], v[140:141], v[68:69]
	v_pk_add_f32 v[142:143], v[142:143], v[70:71]
	global_store_dwordx4 v193, v[144:147], s[86:87]
	global_store_dwordx4 v206, v[140:143], s[86:87]
	v_pk_add_f32 v[136:137], v[136:137], v[76:77]
	v_pk_add_f32 v[138:139], v[138:139], v[78:79]
	v_pk_add_f32 v[132:133], v[132:133], v[80:81]
	v_pk_add_f32 v[134:135], v[134:135], v[82:83]
	global_store_dwordx4 v193, v[136:139], s[86:87] offset:512
	global_store_dwordx4 v206, v[132:135], s[86:87] offset:512
	s_lshl_b32 s94, s51, 8
	s_add_i32 s94, s94, 32
	s_lshl_b32 s94, s94, 14
	s_add_u32 s84, s48, s94
	s_addc_u32 s85, s49, 0
	global_load_dwordx4 v[144:147], v193, s[84:85]
	global_load_dwordx4 v[140:143], v206, s[84:85]
	global_load_dwordx4 v[136:139], v193, s[84:85] offset:512
	global_load_dwordx4 v[132:135], v206, s[84:85] offset:512
	v_mov_b32_dpp v164, v124 row_ror:8 row_mask:0xf bank_mask:0xf
	v_mov_b32_dpp v165, v125 row_ror:8 row_mask:0xf bank_mask:0xf
	v_mov_b32_dpp v166, v126 row_ror:8 row_mask:0xf bank_mask:0xf
	v_mov_b32_dpp v167, v127 row_ror:8 row_mask:0xf bank_mask:0xf
	v_cndmask_b32_e64 v124, v164, v128, s[90:91]
	v_cndmask_b32_e64 v125, v165, v129, s[90:91]
	v_cndmask_b32_e64 v126, v166, v130, s[90:91]
	v_cndmask_b32_e64 v127, v167, v131, s[90:91]
	v_cndmask_b32_e64 v128, v128, v164, s[90:91]
	v_cndmask_b32_e64 v129, v129, v165, s[90:91]
	v_cndmask_b32_e64 v130, v130, v166, s[90:91]
	v_cndmask_b32_e64 v131, v131, v167, s[90:91]
	v_mov_b32_dpp v164, v116 row_ror:8 row_mask:0xf bank_mask:0xf
	v_mov_b32_dpp v165, v117 row_ror:8 row_mask:0xf bank_mask:0xf
	v_mov_b32_dpp v166, v118 row_ror:8 row_mask:0xf bank_mask:0xf
	v_mov_b32_dpp v167, v119 row_ror:8 row_mask:0xf bank_mask:0xf
	v_cndmask_b32_e64 v116, v164, v120, s[90:91]
	v_cndmask_b32_e64 v117, v165, v121, s[90:91]
	v_cndmask_b32_e64 v118, v166, v122, s[90:91]
	v_cndmask_b32_e64 v119, v167, v123, s[90:91]
	v_cndmask_b32_e64 v120, v120, v164, s[90:91]
	v_cndmask_b32_e64 v121, v121, v165, s[90:91]
	v_cndmask_b32_e64 v122, v122, v166, s[90:91]
	v_cndmask_b32_e64 v123, v123, v167, s[90:91]
	s_lshl_b32 s94, s51, 8
	s_add_i32 s94, s94, 16
	s_lshl_b32 s94, s94, 14
	s_add_u32 s86, s48, s94
	s_addc_u32 s87, s49, 0
	s_lshl_b32 s94, s51, 8
	s_add_i32 s94, s94, 16
	s_lshl_b32 s94, s94, 13
	s_add_u32 s88, s12, s94
	s_addc_u32 s89, s13, 0
	s_lshl_b32 s94, s51, 8
	s_add_i32 s94, s94, 16
	s_lshl_b32 s94, s94, 8
	s_add_u32 s92, s22, s94
	s_addc_u32 s93, s23, 0
	s_waitcnt vmcnt(8)
	v_pk_add_f32 v[128:129], v[128:129], v[172:173]
	v_pk_add_f32 v[130:131], v[130:131], v[174:175]
	v_pk_add_f32 v[124:125], v[124:125], v[176:177]
	v_pk_add_f32 v[126:127], v[126:127], v[178:179]
	global_store_dwordx4 v193, v[128:131], s[86:87]
	global_store_dwordx4 v206, v[124:127], s[86:87]
	v_pk_add_f32 v[120:121], v[120:121], v[182:183]
	v_pk_add_f32 v[122:123], v[122:123], v[184:185]
	v_pk_add_f32 v[116:117], v[116:117], v[232:233]
	v_pk_add_f32 v[118:119], v[118:119], v[234:235]
	global_store_dwordx4 v193, v[120:123], s[86:87] offset:512
	global_store_dwordx4 v206, v[116:119], s[86:87] offset:512
	s_lshl_b32 s94, s51, 8
	s_add_i32 s94, s94, 48
	s_lshl_b32 s94, s94, 14
	s_add_u32 s84, s48, s94
	s_addc_u32 s85, s49, 0
	global_load_dwordx4 v[128:131], v193, s[84:85]
	global_load_dwordx4 v[124:127], v206, s[84:85]
	global_load_dwordx4 v[120:123], v193, s[84:85] offset:512
	global_load_dwordx4 v[116:119], v206, s[84:85] offset:512
	v_mov_b32_dpp v164, v108 row_ror:8 row_mask:0xf bank_mask:0xf
	v_mov_b32_dpp v165, v109 row_ror:8 row_mask:0xf bank_mask:0xf
	v_mov_b32_dpp v166, v110 row_ror:8 row_mask:0xf bank_mask:0xf
	v_mov_b32_dpp v167, v111 row_ror:8 row_mask:0xf bank_mask:0xf
	v_cndmask_b32_e64 v108, v164, v112, s[90:91]
	v_cndmask_b32_e64 v109, v165, v113, s[90:91]
	v_cndmask_b32_e64 v110, v166, v114, s[90:91]
	v_cndmask_b32_e64 v111, v167, v115, s[90:91]
	v_cndmask_b32_e64 v112, v112, v164, s[90:91]
	v_cndmask_b32_e64 v113, v113, v165, s[90:91]
	v_cndmask_b32_e64 v114, v114, v166, s[90:91]
	v_cndmask_b32_e64 v115, v115, v167, s[90:91]
	v_mov_b32_dpp v164, v100 row_ror:8 row_mask:0xf bank_mask:0xf
	v_mov_b32_dpp v165, v101 row_ror:8 row_mask:0xf bank_mask:0xf
	v_mov_b32_dpp v166, v102 row_ror:8 row_mask:0xf bank_mask:0xf
	v_mov_b32_dpp v167, v103 row_ror:8 row_mask:0xf bank_mask:0xf
	v_cndmask_b32_e64 v100, v164, v104, s[90:91]
	v_cndmask_b32_e64 v101, v165, v105, s[90:91]
	v_cndmask_b32_e64 v102, v166, v106, s[90:91]
	v_cndmask_b32_e64 v103, v167, v107, s[90:91]
	v_cndmask_b32_e64 v104, v104, v164, s[90:91]
	v_cndmask_b32_e64 v105, v105, v165, s[90:91]
	v_cndmask_b32_e64 v106, v106, v166, s[90:91]
	v_cndmask_b32_e64 v107, v107, v167, s[90:91]
	s_lshl_b32 s94, s51, 8
	s_add_i32 s94, s94, 32
	s_lshl_b32 s94, s94, 14
	s_add_u32 s86, s48, s94
	s_addc_u32 s87, s49, 0
	s_lshl_b32 s94, s51, 8
	s_add_i32 s94, s94, 32
	s_lshl_b32 s94, s94, 13
	s_add_u32 s88, s12, s94
	s_addc_u32 s89, s13, 0
	s_lshl_b32 s94, s51, 8
	s_add_i32 s94, s94, 32
	s_lshl_b32 s94, s94, 8
	s_add_u32 s92, s22, s94
	s_addc_u32 s93, s23, 0
	s_waitcnt vmcnt(8)
	v_pk_add_f32 v[112:113], v[112:113], v[144:145]
	v_pk_add_f32 v[114:115], v[114:115], v[146:147]
	v_pk_add_f32 v[108:109], v[108:109], v[140:141]
	v_pk_add_f32 v[110:111], v[110:111], v[142:143]
	global_store_dwordx4 v193, v[112:115], s[86:87]
	global_store_dwordx4 v206, v[108:111], s[86:87]
	v_pk_add_f32 v[104:105], v[104:105], v[136:137]
	v_pk_add_f32 v[106:107], v[106:107], v[138:139]
	v_pk_add_f32 v[100:101], v[100:101], v[132:133]
	v_pk_add_f32 v[102:103], v[102:103], v[134:135]
	global_store_dwordx4 v193, v[104:107], s[86:87] offset:512
	global_store_dwordx4 v206, v[100:103], s[86:87] offset:512
	s_lshl_b32 s94, s51, 8
	s_add_i32 s94, s94, 128
	s_lshl_b32 s94, s94, 14
	s_add_u32 s84, s48, s94
	s_addc_u32 s85, s49, 0
	global_load_dwordx4 v[112:115], v193, s[84:85]
	global_load_dwordx4 v[108:111], v206, s[84:85]
	global_load_dwordx4 v[104:107], v193, s[84:85] offset:512
	global_load_dwordx4 v[100:103], v206, s[84:85] offset:512
	v_mov_b32_dpp v164, v92 row_ror:8 row_mask:0xf bank_mask:0xf
	v_mov_b32_dpp v165, v93 row_ror:8 row_mask:0xf bank_mask:0xf
	v_mov_b32_dpp v166, v94 row_ror:8 row_mask:0xf bank_mask:0xf
	v_mov_b32_dpp v167, v95 row_ror:8 row_mask:0xf bank_mask:0xf
	v_cndmask_b32_e64 v92, v164, v96, s[90:91]
	v_cndmask_b32_e64 v93, v165, v97, s[90:91]
	v_cndmask_b32_e64 v94, v166, v98, s[90:91]
	v_cndmask_b32_e64 v95, v167, v99, s[90:91]
	v_cndmask_b32_e64 v96, v96, v164, s[90:91]
	v_cndmask_b32_e64 v97, v97, v165, s[90:91]
	v_cndmask_b32_e64 v98, v98, v166, s[90:91]
	v_cndmask_b32_e64 v99, v99, v167, s[90:91]
	v_mov_b32_dpp v164, v84 row_ror:8 row_mask:0xf bank_mask:0xf
	v_mov_b32_dpp v165, v85 row_ror:8 row_mask:0xf bank_mask:0xf
	v_mov_b32_dpp v166, v86 row_ror:8 row_mask:0xf bank_mask:0xf
	v_mov_b32_dpp v167, v87 row_ror:8 row_mask:0xf bank_mask:0xf
	v_cndmask_b32_e64 v84, v164, v88, s[90:91]
	v_cndmask_b32_e64 v85, v165, v89, s[90:91]
	v_cndmask_b32_e64 v86, v166, v90, s[90:91]
	v_cndmask_b32_e64 v87, v167, v91, s[90:91]
	v_cndmask_b32_e64 v88, v88, v164, s[90:91]
	v_cndmask_b32_e64 v89, v89, v165, s[90:91]
	v_cndmask_b32_e64 v90, v90, v166, s[90:91]
	v_cndmask_b32_e64 v91, v91, v167, s[90:91]
	s_lshl_b32 s94, s51, 8
	s_add_i32 s94, s94, 48
	s_lshl_b32 s94, s94, 14
	s_add_u32 s86, s48, s94
	s_addc_u32 s87, s49, 0
	s_lshl_b32 s94, s51, 8
	s_add_i32 s94, s94, 48
	s_lshl_b32 s94, s94, 13
	s_add_u32 s88, s12, s94
	s_addc_u32 s89, s13, 0
	s_lshl_b32 s94, s51, 8
	s_add_i32 s94, s94, 48
	s_lshl_b32 s94, s94, 8
	s_add_u32 s92, s22, s94
	s_addc_u32 s93, s23, 0
	s_waitcnt vmcnt(8)
	v_pk_add_f32 v[96:97], v[96:97], v[128:129]
	v_pk_add_f32 v[98:99], v[98:99], v[130:131]
	v_pk_add_f32 v[92:93], v[92:93], v[124:125]
	v_pk_add_f32 v[94:95], v[94:95], v[126:127]
	global_store_dwordx4 v193, v[96:99], s[86:87]
	global_store_dwordx4 v206, v[92:95], s[86:87]
	v_pk_add_f32 v[88:89], v[88:89], v[120:121]
	v_pk_add_f32 v[90:91], v[90:91], v[122:123]
	v_pk_add_f32 v[84:85], v[84:85], v[116:117]
	v_pk_add_f32 v[86:87], v[86:87], v[118:119]
	global_store_dwordx4 v193, v[88:91], s[86:87] offset:512
	global_store_dwordx4 v206, v[84:87], s[86:87] offset:512
	s_lshl_b32 s94, s51, 8
	s_add_i32 s94, s94, 144
	s_lshl_b32 s94, s94, 14
	s_add_u32 s84, s48, s94
	s_addc_u32 s85, s49, 0
	global_load_dwordx4 v[96:99], v193, s[84:85]
	global_load_dwordx4 v[92:95], v206, s[84:85]
	global_load_dwordx4 v[88:91], v193, s[84:85] offset:512
	global_load_dwordx4 v[84:87], v206, s[84:85] offset:512
	v_mov_b32_dpp v164, v64 row_ror:8 row_mask:0xf bank_mask:0xf
	v_mov_b32_dpp v165, v65 row_ror:8 row_mask:0xf bank_mask:0xf
	v_mov_b32_dpp v166, v66 row_ror:8 row_mask:0xf bank_mask:0xf
	v_mov_b32_dpp v167, v67 row_ror:8 row_mask:0xf bank_mask:0xf
	v_cndmask_b32_e64 v64, v164, v72, s[90:91]
	v_cndmask_b32_e64 v65, v165, v73, s[90:91]
	v_cndmask_b32_e64 v66, v166, v74, s[90:91]
	v_cndmask_b32_e64 v67, v167, v75, s[90:91]
	v_cndmask_b32_e64 v72, v72, v164, s[90:91]
	v_cndmask_b32_e64 v73, v73, v165, s[90:91]
	v_cndmask_b32_e64 v74, v74, v166, s[90:91]
	v_cndmask_b32_e64 v75, v75, v167, s[90:91]
	v_mov_b32_dpp v164, v52 row_ror:8 row_mask:0xf bank_mask:0xf
	v_mov_b32_dpp v165, v53 row_ror:8 row_mask:0xf bank_mask:0xf
	v_mov_b32_dpp v166, v54 row_ror:8 row_mask:0xf bank_mask:0xf
	v_mov_b32_dpp v167, v55 row_ror:8 row_mask:0xf bank_mask:0xf
	v_cndmask_b32_e64 v52, v164, v56, s[90:91]
	v_cndmask_b32_e64 v53, v165, v57, s[90:91]
	v_cndmask_b32_e64 v54, v166, v58, s[90:91]
	v_cndmask_b32_e64 v55, v167, v59, s[90:91]
	v_cndmask_b32_e64 v56, v56, v164, s[90:91]
	v_cndmask_b32_e64 v57, v57, v165, s[90:91]
	v_cndmask_b32_e64 v58, v58, v166, s[90:91]
	v_cndmask_b32_e64 v59, v59, v167, s[90:91]
	s_lshl_b32 s94, s51, 8
	s_add_i32 s94, s94, 128
	s_lshl_b32 s94, s94, 14
	s_add_u32 s86, s48, s94
	s_addc_u32 s87, s49, 0
	s_lshl_b32 s94, s51, 8
	s_add_i32 s94, s94, 128
	s_lshl_b32 s94, s94, 13
	s_add_u32 s88, s12, s94
	s_addc_u32 s89, s13, 0
	s_lshl_b32 s94, s51, 8
	s_add_i32 s94, s94, 128
	s_lshl_b32 s94, s94, 8
	s_add_u32 s92, s22, s94
	s_addc_u32 s93, s23, 0
	s_waitcnt vmcnt(8)
	v_pk_add_f32 v[72:73], v[72:73], v[112:113]
	v_pk_add_f32 v[74:75], v[74:75], v[114:115]
	v_pk_add_f32 v[64:65], v[64:65], v[108:109]
	v_pk_add_f32 v[66:67], v[66:67], v[110:111]
	global_store_dwordx4 v193, v[72:75], s[86:87]
	global_store_dwordx4 v206, v[64:67], s[86:87]
	v_pk_add_f32 v[56:57], v[56:57], v[104:105]
	v_pk_add_f32 v[58:59], v[58:59], v[106:107]
	v_pk_add_f32 v[52:53], v[52:53], v[100:101]
	v_pk_add_f32 v[54:55], v[54:55], v[102:103]
	global_store_dwordx4 v193, v[56:59], s[86:87] offset:512
	global_store_dwordx4 v206, v[52:55], s[86:87] offset:512
	s_lshl_b32 s94, s51, 8
	s_add_i32 s94, s94, 160
	s_lshl_b32 s94, s94, 14
	s_add_u32 s84, s48, s94
	s_addc_u32 s85, s49, 0
	global_load_dwordx4 v[72:75], v193, s[84:85]
	global_load_dwordx4 v[64:67], v206, s[84:85]
	global_load_dwordx4 v[56:59], v193, s[84:85] offset:512
	global_load_dwordx4 v[52:55], v206, s[84:85] offset:512
	v_mov_b32_dpp v164, v44 row_ror:8 row_mask:0xf bank_mask:0xf
	v_mov_b32_dpp v165, v45 row_ror:8 row_mask:0xf bank_mask:0xf
	v_mov_b32_dpp v166, v46 row_ror:8 row_mask:0xf bank_mask:0xf
	v_mov_b32_dpp v167, v47 row_ror:8 row_mask:0xf bank_mask:0xf
	v_cndmask_b32_e64 v44, v164, v48, s[90:91]
	v_cndmask_b32_e64 v45, v165, v49, s[90:91]
	v_cndmask_b32_e64 v46, v166, v50, s[90:91]
	v_cndmask_b32_e64 v47, v167, v51, s[90:91]
	v_cndmask_b32_e64 v48, v48, v164, s[90:91]
	v_cndmask_b32_e64 v49, v49, v165, s[90:91]
	v_cndmask_b32_e64 v50, v50, v166, s[90:91]
	v_cndmask_b32_e64 v51, v51, v167, s[90:91]
	v_mov_b32_dpp v164, v36 row_ror:8 row_mask:0xf bank_mask:0xf
	v_mov_b32_dpp v165, v37 row_ror:8 row_mask:0xf bank_mask:0xf
	v_mov_b32_dpp v166, v38 row_ror:8 row_mask:0xf bank_mask:0xf
	v_mov_b32_dpp v167, v39 row_ror:8 row_mask:0xf bank_mask:0xf
	v_cndmask_b32_e64 v36, v164, v40, s[90:91]
	v_cndmask_b32_e64 v37, v165, v41, s[90:91]
	v_cndmask_b32_e64 v38, v166, v42, s[90:91]
	v_cndmask_b32_e64 v39, v167, v43, s[90:91]
	v_cndmask_b32_e64 v40, v40, v164, s[90:91]
	v_cndmask_b32_e64 v41, v41, v165, s[90:91]
	v_cndmask_b32_e64 v42, v42, v166, s[90:91]
	v_cndmask_b32_e64 v43, v43, v167, s[90:91]
	s_lshl_b32 s94, s51, 8
	s_add_i32 s94, s94, 144
	s_lshl_b32 s94, s94, 14
	s_add_u32 s86, s48, s94
	s_addc_u32 s87, s49, 0
	s_lshl_b32 s94, s51, 8
	s_add_i32 s94, s94, 144
	s_lshl_b32 s94, s94, 13
	s_add_u32 s88, s12, s94
	s_addc_u32 s89, s13, 0
	s_lshl_b32 s94, s51, 8
	s_add_i32 s94, s94, 144
	s_lshl_b32 s94, s94, 8
	s_add_u32 s92, s22, s94
	s_addc_u32 s93, s23, 0
	s_waitcnt vmcnt(8)
	v_pk_add_f32 v[48:49], v[48:49], v[96:97]
	v_pk_add_f32 v[50:51], v[50:51], v[98:99]
	v_pk_add_f32 v[44:45], v[44:45], v[92:93]
	v_pk_add_f32 v[46:47], v[46:47], v[94:95]
	global_store_dwordx4 v193, v[48:51], s[86:87]
	global_store_dwordx4 v206, v[44:47], s[86:87]
	v_pk_add_f32 v[40:41], v[40:41], v[88:89]
	v_pk_add_f32 v[42:43], v[42:43], v[90:91]
	v_pk_add_f32 v[36:37], v[36:37], v[84:85]
	v_pk_add_f32 v[38:39], v[38:39], v[86:87]
	global_store_dwordx4 v193, v[40:43], s[86:87] offset:512
	global_store_dwordx4 v206, v[36:39], s[86:87] offset:512
	s_lshl_b32 s94, s51, 8
	s_add_i32 s94, s94, 176
	s_lshl_b32 s94, s94, 14
	s_add_u32 s84, s48, s94
	s_addc_u32 s85, s49, 0
	global_load_dwordx4 v[48:51], v193, s[84:85]
	global_load_dwordx4 v[44:47], v206, s[84:85]
	global_load_dwordx4 v[40:43], v193, s[84:85] offset:512
	global_load_dwordx4 v[36:39], v206, s[84:85] offset:512
	v_mov_b32_dpp v164, v28 row_ror:8 row_mask:0xf bank_mask:0xf
	v_mov_b32_dpp v165, v29 row_ror:8 row_mask:0xf bank_mask:0xf
	v_mov_b32_dpp v166, v30 row_ror:8 row_mask:0xf bank_mask:0xf
	v_mov_b32_dpp v167, v31 row_ror:8 row_mask:0xf bank_mask:0xf
	v_cndmask_b32_e64 v28, v164, v32, s[90:91]
	v_cndmask_b32_e64 v29, v165, v33, s[90:91]
	v_cndmask_b32_e64 v30, v166, v34, s[90:91]
	v_cndmask_b32_e64 v31, v167, v35, s[90:91]
	v_cndmask_b32_e64 v32, v32, v164, s[90:91]
	v_cndmask_b32_e64 v33, v33, v165, s[90:91]
	v_cndmask_b32_e64 v34, v34, v166, s[90:91]
	v_cndmask_b32_e64 v35, v35, v167, s[90:91]
	v_mov_b32_dpp v164, v20 row_ror:8 row_mask:0xf bank_mask:0xf
	v_mov_b32_dpp v165, v21 row_ror:8 row_mask:0xf bank_mask:0xf
	v_mov_b32_dpp v166, v22 row_ror:8 row_mask:0xf bank_mask:0xf
	v_mov_b32_dpp v167, v23 row_ror:8 row_mask:0xf bank_mask:0xf
	v_cndmask_b32_e64 v20, v164, v24, s[90:91]
	v_cndmask_b32_e64 v21, v165, v25, s[90:91]
	v_cndmask_b32_e64 v22, v166, v26, s[90:91]
	v_cndmask_b32_e64 v23, v167, v27, s[90:91]
	v_cndmask_b32_e64 v24, v24, v164, s[90:91]
	v_cndmask_b32_e64 v25, v25, v165, s[90:91]
	v_cndmask_b32_e64 v26, v26, v166, s[90:91]
	v_cndmask_b32_e64 v27, v27, v167, s[90:91]
	s_lshl_b32 s94, s51, 8
	s_add_i32 s94, s94, 160
	s_lshl_b32 s94, s94, 14
	s_add_u32 s86, s48, s94
	s_addc_u32 s87, s49, 0
	s_lshl_b32 s94, s51, 8
	s_add_i32 s94, s94, 160
	s_lshl_b32 s94, s94, 13
	s_add_u32 s88, s12, s94
	s_addc_u32 s89, s13, 0
	s_lshl_b32 s94, s51, 8
	s_add_i32 s94, s94, 160
	s_lshl_b32 s94, s94, 8
	s_add_u32 s92, s22, s94
	s_addc_u32 s93, s23, 0
	s_waitcnt vmcnt(8)
	v_pk_add_f32 v[32:33], v[32:33], v[72:73]
	v_pk_add_f32 v[34:35], v[34:35], v[74:75]
	v_pk_add_f32 v[28:29], v[28:29], v[64:65]
	v_pk_add_f32 v[30:31], v[30:31], v[66:67]
	global_store_dwordx4 v193, v[32:35], s[86:87]
	global_store_dwordx4 v206, v[28:31], s[86:87]
	v_pk_add_f32 v[24:25], v[24:25], v[56:57]
	v_pk_add_f32 v[26:27], v[26:27], v[58:59]
	v_pk_add_f32 v[20:21], v[20:21], v[52:53]
	v_pk_add_f32 v[22:23], v[22:23], v[54:55]
	global_store_dwordx4 v193, v[24:27], s[86:87] offset:512
	global_store_dwordx4 v206, v[20:23], s[86:87] offset:512
	v_mov_b32_dpp v164, v12 row_ror:8 row_mask:0xf bank_mask:0xf
	v_mov_b32_dpp v165, v13 row_ror:8 row_mask:0xf bank_mask:0xf
	v_mov_b32_dpp v166, v14 row_ror:8 row_mask:0xf bank_mask:0xf
	v_mov_b32_dpp v167, v15 row_ror:8 row_mask:0xf bank_mask:0xf
	v_cndmask_b32_e64 v12, v164, v16, s[90:91]
	v_cndmask_b32_e64 v13, v165, v17, s[90:91]
	v_cndmask_b32_e64 v14, v166, v18, s[90:91]
	v_cndmask_b32_e64 v15, v167, v19, s[90:91]
	v_cndmask_b32_e64 v16, v16, v164, s[90:91]
	v_cndmask_b32_e64 v17, v17, v165, s[90:91]
	v_cndmask_b32_e64 v18, v18, v166, s[90:91]
	v_cndmask_b32_e64 v19, v19, v167, s[90:91]
	v_mov_b32_dpp v164, v4 row_ror:8 row_mask:0xf bank_mask:0xf
	v_mov_b32_dpp v165, v5 row_ror:8 row_mask:0xf bank_mask:0xf
	v_mov_b32_dpp v166, v6 row_ror:8 row_mask:0xf bank_mask:0xf
	v_mov_b32_dpp v167, v7 row_ror:8 row_mask:0xf bank_mask:0xf
	v_cndmask_b32_e64 v4, v164, v8, s[90:91]
	v_cndmask_b32_e64 v5, v165, v9, s[90:91]
	v_cndmask_b32_e64 v6, v166, v10, s[90:91]
	v_cndmask_b32_e64 v7, v167, v11, s[90:91]
	v_cndmask_b32_e64 v8, v8, v164, s[90:91]
	v_cndmask_b32_e64 v9, v9, v165, s[90:91]
	v_cndmask_b32_e64 v10, v10, v166, s[90:91]
	v_cndmask_b32_e64 v11, v11, v167, s[90:91]
	s_lshl_b32 s94, s51, 8
	s_add_i32 s94, s94, 176
	s_lshl_b32 s94, s94, 14
	s_add_u32 s86, s48, s94
	s_addc_u32 s87, s49, 0
	s_lshl_b32 s94, s51, 8
	s_add_i32 s94, s94, 176
	s_lshl_b32 s94, s94, 13
	s_add_u32 s88, s12, s94
	s_addc_u32 s89, s13, 0
	s_lshl_b32 s94, s51, 8
	s_add_i32 s94, s94, 176
	s_lshl_b32 s94, s94, 8
	s_add_u32 s92, s22, s94
	s_addc_u32 s93, s23, 0
	s_waitcnt vmcnt(4)
	v_pk_add_f32 v[16:17], v[16:17], v[48:49]
	v_pk_add_f32 v[18:19], v[18:19], v[50:51]
	v_pk_add_f32 v[12:13], v[12:13], v[44:45]
	v_pk_add_f32 v[14:15], v[14:15], v[46:47]
	global_store_dwordx4 v193, v[16:19], s[86:87]
	global_store_dwordx4 v206, v[12:15], s[86:87]
	v_pk_add_f32 v[8:9], v[8:9], v[40:41]
	v_pk_add_f32 v[10:11], v[10:11], v[42:43]
	v_pk_add_f32 v[4:5], v[4:5], v[36:37]
	v_pk_add_f32 v[6:7], v[6:7], v[38:39]
	global_store_dwordx4 v193, v[8:11], s[86:87] offset:512
	global_store_dwordx4 v206, v[4:7], s[86:87] offset:512
.Lp8epi_end:
	v_mov_b32_e32 v232, 0x6c0
	v_mov_b32_e32 v233, 0x750
	v_mov_b32_e32 v234, 0x7e0
	v_mov_b32_e32 v235, 0x870
